# P15 panel hand-off: L1 invalidate issued early by wave 1
# baseline (speedup 1.0000x reference)
.LBB0_1534:
	s_or_b64 exec, exec, s[0:1]
	s_waitcnt vmcnt(0)
	v_or_b32_e32 v36, s33, v162
	v_cmp_eq_u32_e32 vcc, 0, v36
	s_barrier
	s_cmp_lg_u32 s33, 1
	s_cbranch_scc1 .Lb6_skip
	s_mov_b64 s[98:99], exec
	s_mov_b64 exec, -1
	buffer_inv sc1
	s_waitcnt vmcnt(0)
	s_mov_b64 exec, s[98:99]
.Lb6_skip:
	s_and_saveexec_b64 s[0:1], vcc
	s_cbranch_execz .LBB0_1546
	s_lshl_b32 s12, s12, 6
	s_ashr_i32 s13, s12, 31
	s_lshl_b64 s[12:13], s[12:13], 2
	s_mov_b64 s[8:9], exec
	s_add_u32 s6, s6, s12
	buffer_wbl2 sc1
	s_waitcnt vmcnt(0)
	s_waitcnt vmcnt(0)
	s_addc_u32 s7, s7, s13
	v_mbcnt_lo_u32_b32 v36, s8, 0
	s_add_u32 s6, s6, 0x1e04000
	v_mbcnt_hi_u32_b32 v36, s9, v36
	s_addc_u32 s7, s7, 0
	v_cmp_eq_u32_e32 vcc, 0, v36
	s_and_saveexec_b64 s[12:13], vcc
	s_cbranch_execz .LBB0_1537
	s_bcnt1_i32_b64 s8, s[8:9]
	v_mov_b32_e32 v36, 0
	v_mov_b32_e32 v37, s8
	global_atomic_add v36, v37, s[6:7]

.LBB0_1539:
	global_load_dword v37, v36, s[6:7] sc1
	s_mov_b64 s[8:9], -1
	s_waitcnt vmcnt(0)
	v_cmp_lt_u32_e32 vcc, 3, v37
	s_cbranch_vccnz .LBB0_1538
	s_sleep 2
	global_load_dword v37, v36, s[6:7] sc1
	s_waitcnt vmcnt(0)
	v_cmp_gt_u32_e32 vcc, 4, v37
	s_cbranch_vccz .LBB0_1538
	s_sleep 2
	global_load_dword v37, v36, s[6:7] sc1
	s_waitcnt vmcnt(0)
	v_cmp_gt_u32_e32 vcc, 4, v37
	s_cbranch_vccz .LBB0_1538
	s_sleep 2
	global_load_dword v37, v36, s[6:7] sc1
	s_waitcnt vmcnt(0)
	v_cmp_gt_u32_e32 vcc, 4, v37
	s_cbranch_vccz .LBB0_1538
	s_sleep 2
	global_load_dword v37, v36, s[6:7] sc1
	s_waitcnt vmcnt(0)
	v_cmp_gt_u32_e32 vcc, 4, v37
	s_cbranch_vccz .LBB0_1538
	s_add_i32 s12, s12, -5
	s_cmp_eq_u32 s12, 0
	s_cselect_b64 s[8:9], -1, 0
	s_sleep 2
	s_branch .LBB0_1538
.LBB0_1545:
	s_nop 0
	s_waitcnt vmcnt(0)
.LBB0_1546:
	s_or_b64 exec, exec, s[0:1]
	s_lshl_b32 s19, s33, 3
	s_lshl_b32 s0, s33, 4
	s_andn2_b32 s0, s0, 63
	s_and_b32 s1, s19, 16
	v_lshl_or_b32 v36, s38, 5, v163
	s_or_b32 s9, s1, s0
	s_movk_i32 s0, 0x410
	v_mul_lo_u32 v36, v36, s0
	s_lshl_b32 s0, s39, 7
	v_lshlrev_b32_e32 v37, 1, v162
	s_and_b32 s8, s19, 8
	v_and_b32_e32 v37, 0xffffffe0, v37
	s_add_i32 s0, s0, 0
	s_add_i32 s12, s16, s9
	v_add3_u32 v136, s0, v36, v37
	s_or_b32 s0, s12, s8
	s_ashr_i32 s1, s0, 31
	s_lshl_b64 s[0:1], s[0:1], 4
	s_add_u32 s0, s4, s0
	s_barrier
	ds_write_b128 v136, v[128:131]
	ds_write_b128 v136, v[124:127] offset:16
	ds_write_b128 v136, v[120:123] offset:512
	ds_write_b128 v136, v[112:115] offset:528
	ds_write_b128 v136, v[116:119] offset:16640
	ds_write_b128 v136, v[108:111] offset:16656
	ds_write_b128 v136, v[104:107] offset:17152
	ds_write_b128 v136, v[132:135] offset:17168
	s_addc_u32 s1, s5, s1
	v_mov_b32_e32 v113, 0
	s_waitcnt lgkmcnt(0)
	s_barrier
	global_load_dwordx4 v[116:119], v113, s[0:1]
	global_load_dwordx4 v[120:123], v113, s[0:1] offset:16
	global_load_dwordx4 v[124:127], v113, s[0:1] offset:48
	global_load_dwordx4 v[128:131], v113, s[0:1] offset:32
	s_mov_b32 s0, 0x358637bd
	s_or_b32 s13, s8, 4
	v_mov_b64_e32 v[110:111], s[0:1]
	s_or_b32 s0, s12, s13
	s_ashr_i32 s1, s0, 31
	s_lshl_b64 s[0:1], s[0:1], 4
	v_lshl_add_u32 v112, v162, 4, 0
	s_mulk_i32 s33, 0x2080
	s_add_u32 s0, s4, s0
	v_add_u32_e32 v114, s33, v112
	s_addc_u32 s1, s5, s1
	ds_read_b128 v[132:135], v114
	global_load_dwordx4 v[36:39], v113, s[0:1] offset:48
	global_load_dwordx4 v[104:107], v113, s[0:1] offset:32
	global_load_dwordx4 v[138:141], v113, s[0:1] offset:16
	global_load_dwordx4 v[142:145], v113, s[0:1]
	s_or_b32 s12, s16, s8
	s_add_i32 s0, s12, s9
	s_ashr_i32 s1, s0, 31
	s_lshl_b64 s[0:1], s[0:1], 12
	s_add_u32 s0, s10, s0
	s_addc_u32 s1, s11, s1
	s_mov_b32 s6, 0x3a800000
	s_mov_b32 s7, 0x800000
	s_add_u32 s0, s0, s2
	v_lshlrev_b64 v[108:109], 2, v[156:157]
	s_addc_u32 s1, s1, s3
	v_lshl_add_u64 v[146:147], s[0:1], 0, v[108:109]
	s_or_b32 s14, s19, 1
	s_and_b32 s15, s14, 9
	s_mulk_i32 s14, 0x410
	v_add_u32_e32 v112, s14, v112
	s_waitcnt vmcnt(7)
	v_mov_b32_e32 v148, v117
	v_mov_b32_e32 v149, v118
	v_mov_b32_e32 v117, v119
	s_waitcnt vmcnt(6)
	v_mov_b32_e32 v118, v121
	v_mov_b32_e32 v119, v122
	v_mov_b32_e32 v121, v123
	v_pk_add_f32 v[116:117], v[148:149], v[116:117]
	v_pk_add_f32 v[118:119], v[118:119], v[120:121]
	v_mov_b32_e32 v121, v116
	v_mov_b32_e32 v120, v118
	v_mov_b32_e32 v116, v119
	v_pk_add_f32 v[116:117], v[120:121], v[116:117]
	s_nop 0
	v_pk_fma_f32 v[116:117], v[116:117], s[6:7], v[110:111] op_sel_hi:[1,0,0]
	s_nop 0
	v_mul_f32_e32 v118, 0x4b800000, v116
	v_cmp_gt_f32_e64 s[0:1], s7, v116
	v_mul_f32_e32 v115, 0x4b800000, v117
	v_cmp_gt_f32_e32 vcc, s7, v117
	v_cndmask_b32_e64 v116, v116, v118, s[0:1]
	v_rsq_f32_e32 v137, v116
	v_cndmask_b32_e32 v115, v117, v115, vcc
	v_rsq_f32_e32 v115, v115
	ds_read_b128 v[116:119], v112
	ds_read_b128 v[120:123], v112 offset:1040
	v_mul_f32_e32 v149, 0x45800000, v137
	v_cndmask_b32_e64 v150, v137, v149, s[0:1]
	s_or_b32 s0, s16, s15
	s_add_i32 s14, s0, s9
	s_ashr_i32 s15, s14, 31
	s_lshl_b64 s[14:15], s[14:15], 12
	v_mul_f32_e32 v148, 0x45800000, v115
	s_add_u32 s1, s10, s14
	v_cndmask_b32_e32 v148, v115, v148, vcc
	s_addc_u32 s15, s11, s15
	s_waitcnt lgkmcnt(2)
	v_pk_mul_f32 v[132:133], v[132:133], v[148:149] op_sel_hi:[1,0]
	v_pk_mul_f32 v[134:135], v[134:135], v[148:149] op_sel_hi:[1,0]
	s_add_u32 s14, s1, s2
	s_waitcnt lgkmcnt(1)
	v_pk_mul_f32 v[148:149], v[116:117], v[150:151] op_sel_hi:[1,0]
	v_pk_mul_f32 v[150:151], v[118:119], v[150:151] op_sel_hi:[1,0]
	v_pk_mul_f32 v[118:119], v[2:3], v[134:135]
	v_pk_mul_f32 v[116:117], v[0:1], v[132:133]
	s_addc_u32 s15, s15, s3
	global_store_dwordx4 v[146:147], v[116:119], off
	v_lshl_add_u64 v[132:133], s[14:15], 0, v[108:109]
	s_or_b32 s1, s19, 2
	v_pk_mul_f32 v[118:119], v[2:3], v[150:151]
	v_pk_mul_f32 v[116:117], v[0:1], v[148:149]
	global_store_dwordx4 v[132:133], v[116:119], off
	s_and_b32 s1, s1, 10
	s_or_b32 s1, s16, s1
	s_waitcnt vmcnt(6)
	v_mov_b32_e32 v116, v129
	v_mov_b32_e32 v117, v130
	v_mov_b32_e32 v129, v131
	v_mov_b32_e32 v118, v125
	v_mov_b32_e32 v119, v126
	v_mov_b32_e32 v125, v127
	v_pk_add_f32 v[116:117], v[116:117], v[128:129]
	v_pk_add_f32 v[118:119], v[118:119], v[124:125]
	v_mov_b32_e32 v125, v116
	v_mov_b32_e32 v124, v118
	v_mov_b32_e32 v116, v119
	v_pk_add_f32 v[116:117], v[124:125], v[116:117]
	s_add_i32 s14, s1, s9
	v_pk_fma_f32 v[124:125], v[116:117], s[6:7], v[110:111] op_sel_hi:[1,0,0]
	s_ashr_i32 s15, s14, 31
	v_mul_f32_e32 v115, 0x4b800000, v125
	v_cmp_gt_f32_e32 vcc, s7, v125
	s_lshl_b64 s[14:15], s[14:15], 12
	s_add_u32 s14, s10, s14
	v_cndmask_b32_e32 v115, v125, v115, vcc
	v_rsq_f32_e32 v115, v115
	s_addc_u32 s15, s11, s15
	s_add_u32 s14, s14, s2
	s_addc_u32 s15, s15, s3
	v_lshl_add_u64 v[128:129], s[14:15], 0, v[108:109]
	s_or_b32 s14, s19, 3
	v_mul_f32_e32 v125, 0x45800000, v115
	s_and_b32 s14, s14, 11
	v_cndmask_b32_e32 v126, v115, v125, vcc
	v_mul_f32_e32 v115, 0x4b800000, v124
	v_cmp_gt_f32_e32 vcc, s7, v124
	s_or_b32 s14, s16, s14
	s_add_i32 s20, s14, s9
	v_cndmask_b32_e32 v115, v124, v115, vcc
	v_rsq_f32_e32 v115, v115
	ds_read_b128 v[116:119], v112 offset:2080
	s_ashr_i32 s21, s20, 31
	s_waitcnt lgkmcnt(1)
	v_pk_mul_f32 v[120:121], v[120:121], v[126:127] op_sel_hi:[1,0]
	v_pk_mul_f32 v[122:123], v[122:123], v[126:127] op_sel_hi:[1,0]
	s_lshl_b64 s[20:21], s[20:21], 12
	v_pk_mul_f32 v[122:123], v[2:3], v[122:123]
	v_pk_mul_f32 v[120:121], v[0:1], v[120:121]
	s_add_u32 s15, s10, s20
	global_store_dwordx4 v[128:129], v[120:123], off
	s_addc_u32 s17, s11, s21
	s_add_u32 s20, s15, s2
	v_mul_f32_e32 v120, 0x45800000, v115
	v_cndmask_b32_e32 v124, v115, v120, vcc
	ds_read_b128 v[120:123], v112 offset:3120
	s_waitcnt lgkmcnt(1)
	v_pk_mul_f32 v[116:117], v[116:117], v[124:125] op_sel_hi:[1,0]
	v_pk_mul_f32 v[118:119], v[118:119], v[124:125] op_sel_hi:[1,0]
	s_addc_u32 s21, s17, s3
	v_pk_mul_f32 v[118:119], v[2:3], v[118:119]
	v_pk_mul_f32 v[116:117], v[0:1], v[116:117]
	v_lshl_add_u64 v[124:125], s[20:21], 0, v[108:109]
	global_store_dwordx4 v[124:125], v[116:119], off
	s_or_b32 s15, s19, 4
	s_and_b32 s15, s15, 12
	s_waitcnt vmcnt(4)
	v_mov_b32_e32 v116, v143
	v_mov_b32_e32 v117, v144
	v_mov_b32_e32 v143, v145
	v_mov_b32_e32 v118, v139
	v_mov_b32_e32 v119, v140
	v_mov_b32_e32 v139, v141
	v_pk_add_f32 v[116:117], v[116:117], v[142:143]
	v_pk_add_f32 v[118:119], v[118:119], v[138:139]
	v_mov_b32_e32 v127, v116
	v_mov_b32_e32 v126, v118
	v_mov_b32_e32 v116, v119
	v_pk_add_f32 v[116:117], v[126:127], v[116:117]
	s_or_b32 s15, s16, s15
	v_pk_fma_f32 v[126:127], v[116:117], s[6:7], v[110:111] op_sel_hi:[1,0,0]
	s_add_i32 s20, s15, s9
	v_mul_f32_e32 v115, 0x4b800000, v127
	v_cmp_gt_f32_e32 vcc, s7, v127
	s_ashr_i32 s21, s20, 31
	s_lshl_b64 s[20:21], s[20:21], 12
	v_cndmask_b32_e32 v115, v127, v115, vcc
	v_rsq_f32_e32 v115, v115
	s_add_u32 s17, s10, s20
	s_addc_u32 s18, s11, s21
	s_add_u32 s20, s17, s2
	s_addc_u32 s21, s18, s3
	s_or_b32 s17, s19, 5
	v_mul_f32_e32 v127, 0x45800000, v115
	s_and_b32 s17, s17, 13
	v_cndmask_b32_e32 v128, v115, v127, vcc
	v_mul_f32_e32 v115, 0x4b800000, v126
	v_cmp_gt_f32_e32 vcc, s7, v126
	s_or_b32 s17, s16, s17
	v_lshl_add_u64 v[124:125], s[20:21], 0, v[108:109]
	v_cndmask_b32_e32 v115, v126, v115, vcc
	v_rsq_f32_e32 v115, v115
	s_add_i32 s20, s17, s9
	ds_read_b128 v[116:119], v112 offset:4160
	s_ashr_i32 s21, s20, 31
	s_waitcnt lgkmcnt(1)
	v_pk_mul_f32 v[120:121], v[128:129], v[120:121] op_sel_hi:[0,1]
	v_pk_mul_f32 v[122:123], v[128:129], v[122:123] op_sel_hi:[0,1]
	s_lshl_b64 s[20:21], s[20:21], 12
	v_pk_mul_f32 v[122:123], v[2:3], v[122:123]
	v_pk_mul_f32 v[120:121], v[0:1], v[120:121]
	s_add_u32 s18, s10, s20
	global_store_dwordx4 v[124:125], v[120:123], off
	s_addc_u32 s21, s11, s21
	s_add_u32 s20, s18, s2
	v_mul_f32_e32 v120, 0x45800000, v115
	v_cndmask_b32_e32 v124, v115, v120, vcc
	ds_read_b128 v[120:123], v112 offset:5200
	s_waitcnt lgkmcnt(1)
	v_pk_mul_f32 v[116:117], v[124:125], v[116:117] op_sel_hi:[0,1]
	v_pk_mul_f32 v[118:119], v[124:125], v[118:119] op_sel_hi:[0,1]
	s_addc_u32 s21, s21, s3
	v_pk_mul_f32 v[118:119], v[2:3], v[118:119]
	v_pk_mul_f32 v[116:117], v[0:1], v[116:117]
	v_lshl_add_u64 v[124:125], s[20:21], 0, v[108:109]
	global_store_dwordx4 v[124:125], v[116:119], off
	s_or_b32 s18, s19, 6
	s_and_b32 s18, s18, 14
	v_mov_b32_e32 v116, v105
	v_mov_b32_e32 v117, v106
	v_mov_b32_e32 v105, v107
	v_mov_b32_e32 v106, v37
	v_mov_b32_e32 v107, v38
	v_mov_b32_e32 v37, v39
	v_pk_add_f32 v[104:105], v[116:117], v[104:105]
	v_pk_add_f32 v[36:37], v[106:107], v[36:37]
	v_mov_b32_e32 v39, v104
	v_mov_b32_e32 v38, v36
	v_mov_b32_e32 v104, v37
	s_or_b32 s18, s16, s18
	v_pk_add_f32 v[36:37], v[38:39], v[104:105]
	s_add_i32 s20, s18, s9
	v_pk_fma_f32 v[104:105], v[36:37], s[6:7], v[110:111] op_sel_hi:[1,0,0]
	s_ashr_i32 s21, s20, 31
	v_mul_f32_e32 v36, 0x4b800000, v105
	v_cmp_gt_f32_e32 vcc, s7, v105
	s_lshl_b64 s[20:21], s[20:21], 12
	s_add_u32 s20, s10, s20
	v_cndmask_b32_e32 v36, v105, v36, vcc
	v_rsq_f32_e32 v105, v36
	s_addc_u32 s21, s11, s21
	s_add_u32 s20, s20, s2
	s_addc_u32 s21, s21, s3
	s_or_b32 s19, s19, 7
	s_and_b32 s19, s19, 15
	v_mul_f32_e32 v106, 0x45800000, v105
	v_cndmask_b32_e32 v106, v105, v106, vcc
	v_mul_f32_e32 v105, 0x4b800000, v104
	v_cmp_gt_f32_e32 vcc, s7, v104
	s_or_b32 s19, s16, s19
	v_lshl_add_u64 v[116:117], s[20:21], 0, v[108:109]
	v_cndmask_b32_e32 v104, v104, v105, vcc
	s_add_i32 s20, s19, s9
	v_rsq_f32_e32 v115, v104
	s_ashr_i32 s21, s20, 31
	ds_read_b128 v[36:39], v112 offset:6240
	s_lshl_b64 s[20:21], s[20:21], 12
	s_waitcnt lgkmcnt(1)
	v_pk_mul_f32 v[118:119], v[106:107], v[120:121] op_sel_hi:[0,1]
	v_pk_mul_f32 v[106:107], v[106:107], v[122:123] op_sel_hi:[0,1]
	s_add_u32 s20, s10, s20
	v_pk_mul_f32 v[106:107], v[2:3], v[106:107]
	v_pk_mul_f32 v[104:105], v[0:1], v[118:119]
	s_addc_u32 s21, s11, s21
	global_store_dwordx4 v[116:117], v[104:107], off
	s_add_u32 s20, s20, s2
	s_addc_u32 s21, s21, s3
	v_mul_f32_e32 v104, 0x45800000, v115
	v_cndmask_b32_e32 v104, v115, v104, vcc
	s_waitcnt lgkmcnt(0)
	v_pk_mul_f32 v[36:37], v[104:105], v[36:37] op_sel_hi:[0,1]
	v_pk_mul_f32 v[38:39], v[104:105], v[38:39] op_sel_hi:[0,1]
	v_lshl_add_u64 v[104:105], s[20:21], 0, v[108:109]
	s_or_b32 s20, s9, 32
	s_add_i32 s21, s16, s20
	s_or_b32 s22, s21, s8
	s_ashr_i32 s23, s22, 31
	s_lshl_b64 s[22:23], s[22:23], 4
	s_add_u32 s22, s4, s22
	v_pk_mul_f32 v[38:39], v[2:3], v[38:39]
	v_pk_mul_f32 v[36:37], v[0:1], v[36:37]
	s_addc_u32 s23, s5, s23
	global_store_dwordx4 v[104:105], v[36:39], off
	s_barrier
	ds_write_b128 v136, v[96:99]
	ds_write_b128 v136, v[92:95] offset:16
	ds_write_b128 v136, v[88:91] offset:512
	ds_write_b128 v136, v[80:83] offset:528
	ds_write_b128 v136, v[84:87] offset:16640
	ds_write_b128 v136, v[76:79] offset:16656
	ds_write_b128 v136, v[72:75] offset:17152
	ds_write_b128 v136, v[100:103] offset:17168
	s_waitcnt lgkmcnt(0)
	s_barrier
	global_load_dwordx4 v[76:79], v113, s[22:23]
	global_load_dwordx4 v[80:83], v113, s[22:23] offset:16
	global_load_dwordx4 v[84:87], v113, s[22:23] offset:32
	global_load_dwordx4 v[88:91], v113, s[22:23] offset:48
	s_or_b32 s22, s21, s13
	s_ashr_i32 s23, s22, 31
	s_lshl_b64 s[22:23], s[22:23], 4
	s_add_u32 s22, s4, s22
	s_addc_u32 s23, s5, s23
	global_load_dwordx4 v[36:39], v113, s[22:23] offset:48
	global_load_dwordx4 v[72:75], v113, s[22:23] offset:32
	global_load_dwordx4 v[92:95], v113, s[22:23] offset:16
	global_load_dwordx4 v[96:99], v113, s[22:23]
	s_add_i32 s22, s12, s20
	s_ashr_i32 s23, s22, 31
	ds_read_b128 v[100:103], v114
	s_lshl_b64 s[22:23], s[22:23], 12
	s_add_u32 s21, s10, s22
	s_addc_u32 s23, s11, s23
	s_add_u32 s22, s21, s2
	s_addc_u32 s23, s23, s3
	s_waitcnt vmcnt(7)
	v_mov_b32_e32 v104, v77
	v_mov_b32_e32 v105, v78
	v_mov_b32_e32 v77, v79
	s_waitcnt vmcnt(6)
	v_mov_b32_e32 v78, v81
	v_mov_b32_e32 v79, v82
	v_mov_b32_e32 v81, v83
	v_pk_add_f32 v[76:77], v[104:105], v[76:77]
	v_pk_add_f32 v[78:79], v[78:79], v[80:81]
	v_mov_b32_e32 v81, v76
	v_mov_b32_e32 v80, v78
	v_mov_b32_e32 v76, v79
	v_pk_add_f32 v[76:77], v[80:81], v[76:77]
	v_lshl_add_u64 v[104:105], s[22:23], 0, v[108:109]
	v_pk_fma_f32 v[80:81], v[76:77], s[6:7], v[110:111] op_sel_hi:[1,0,0]
	s_add_i32 s22, s0, s20
	v_mul_f32_e32 v76, 0x4b800000, v81
	v_cmp_gt_f32_e32 vcc, s7, v81
	s_ashr_i32 s23, s22, 31
	s_lshl_b64 s[22:23], s[22:23], 12
	v_cndmask_b32_e32 v76, v81, v76, vcc
	v_rsq_f32_e32 v81, v76
	ds_read_b128 v[76:79], v112
	s_add_u32 s21, s10, s22
	s_addc_u32 s23, s11, s23
	v_mul_f32_e32 v82, 0x45800000, v81
	v_cndmask_b32_e32 v82, v81, v82, vcc
	v_mul_f32_e32 v81, 0x4b800000, v80
	v_cmp_gt_f32_e32 vcc, s7, v80
	s_waitcnt lgkmcnt(1)
	v_pk_mul_f32 v[100:101], v[100:101], v[82:83] op_sel_hi:[1,0]
	v_pk_mul_f32 v[82:83], v[102:103], v[82:83] op_sel_hi:[1,0]
	v_cndmask_b32_e32 v80, v80, v81, vcc
	v_rsq_f32_e32 v102, v80
	v_pk_mul_f32 v[82:83], v[2:3], v[82:83]
	v_pk_mul_f32 v[80:81], v[0:1], v[100:101]
	global_store_dwordx4 v[104:105], v[80:83], off
	s_add_u32 s22, s21, s2
	s_addc_u32 s23, s23, s3
	v_mul_f32_e32 v80, 0x45800000, v102
	v_cndmask_b32_e32 v100, v102, v80, vcc
	ds_read_b128 v[80:83], v112 offset:1040
	s_waitcnt lgkmcnt(1)
	v_pk_mul_f32 v[76:77], v[76:77], v[100:101] op_sel_hi:[1,0]
	v_pk_mul_f32 v[78:79], v[78:79], v[100:101] op_sel_hi:[1,0]
	v_pk_mul_f32 v[76:77], v[0:1], v[76:77]
	v_pk_mul_f32 v[78:79], v[2:3], v[78:79]
	v_lshl_add_u64 v[100:101], s[22:23], 0, v[108:109]
	global_store_dwordx4 v[100:101], v[76:79], off
	s_add_i32 s22, s1, s20
	s_ashr_i32 s23, s22, 31
	s_waitcnt vmcnt(7)
	v_mov_b32_e32 v76, v85
	v_mov_b32_e32 v77, v86
	v_mov_b32_e32 v85, v87
	s_waitcnt vmcnt(6)
	v_mov_b32_e32 v78, v89
	v_mov_b32_e32 v79, v90
	v_mov_b32_e32 v89, v91
	v_pk_add_f32 v[76:77], v[76:77], v[84:85]
	v_pk_add_f32 v[78:79], v[78:79], v[88:89]
	v_mov_b32_e32 v85, v76
	v_mov_b32_e32 v84, v78
	v_mov_b32_e32 v76, v79
	v_pk_add_f32 v[76:77], v[84:85], v[76:77]
	s_lshl_b64 s[22:23], s[22:23], 12
	v_pk_fma_f32 v[84:85], v[76:77], s[6:7], v[110:111] op_sel_hi:[1,0,0]
	s_add_u32 s21, s10, s22
	v_mul_f32_e32 v76, 0x4b800000, v85
	v_cmp_gt_f32_e32 vcc, s7, v85
	s_addc_u32 s23, s11, s23
	s_add_u32 s22, s21, s2
	v_cndmask_b32_e32 v76, v85, v76, vcc
	v_rsq_f32_e32 v85, v76
	s_addc_u32 s23, s23, s3
	v_lshl_add_u64 v[86:87], s[22:23], 0, v[108:109]
	s_add_i32 s22, s14, s20
	v_mul_f32_e32 v88, 0x45800000, v85
	v_cndmask_b32_e32 v88, v85, v88, vcc
	v_mul_f32_e32 v85, 0x4b800000, v84
	v_cmp_gt_f32_e32 vcc, s7, v84
	ds_read_b128 v[76:79], v112 offset:2080
	s_ashr_i32 s23, s22, 31
	v_cndmask_b32_e32 v84, v84, v85, vcc
	v_rsq_f32_e32 v84, v84
	s_waitcnt lgkmcnt(1)
	v_pk_mul_f32 v[80:81], v[80:81], v[88:89] op_sel_hi:[1,0]
	v_pk_mul_f32 v[82:83], v[82:83], v[88:89] op_sel_hi:[1,0]
	s_lshl_b64 s[22:23], s[22:23], 12
	v_pk_mul_f32 v[82:83], v[2:3], v[82:83]
	v_pk_mul_f32 v[80:81], v[0:1], v[80:81]
	s_add_u32 s21, s10, s22
	global_store_dwordx4 v[86:87], v[80:83], off
	s_addc_u32 s23, s11, s23
	s_add_u32 s22, s21, s2
	v_mul_f32_e32 v80, 0x45800000, v84
	v_cndmask_b32_e32 v84, v84, v80, vcc
	ds_read_b128 v[80:83], v112 offset:3120
	s_waitcnt lgkmcnt(1)
	v_pk_mul_f32 v[76:77], v[76:77], v[84:85] op_sel_hi:[1,0]
	v_pk_mul_f32 v[78:79], v[78:79], v[84:85] op_sel_hi:[1,0]
	s_addc_u32 s23, s23, s3
	v_pk_mul_f32 v[78:79], v[2:3], v[78:79]
	v_pk_mul_f32 v[76:77], v[0:1], v[76:77]
	v_lshl_add_u64 v[84:85], s[22:23], 0, v[108:109]
	global_store_dwordx4 v[84:85], v[76:79], off
	s_add_i32 s22, s15, s20
	s_ashr_i32 s23, s22, 31
	s_waitcnt vmcnt(4)
	v_mov_b32_e32 v76, v97
	v_mov_b32_e32 v77, v98
	v_mov_b32_e32 v97, v99
	v_mov_b32_e32 v78, v93
	v_mov_b32_e32 v79, v94
	v_mov_b32_e32 v93, v95
	v_pk_add_f32 v[76:77], v[76:77], v[96:97]
	v_pk_add_f32 v[78:79], v[78:79], v[92:93]
	v_mov_b32_e32 v85, v76
	v_mov_b32_e32 v84, v78
	v_mov_b32_e32 v76, v79
	v_pk_add_f32 v[76:77], v[84:85], v[76:77]
	s_lshl_b64 s[22:23], s[22:23], 12
	v_pk_fma_f32 v[84:85], v[76:77], s[6:7], v[110:111] op_sel_hi:[1,0,0]
	s_add_u32 s21, s10, s22
	v_mul_f32_e32 v76, 0x4b800000, v85
	v_cmp_gt_f32_e32 vcc, s7, v85
	s_addc_u32 s23, s11, s23
	s_add_u32 s22, s21, s2
	v_cndmask_b32_e32 v76, v85, v76, vcc
	v_rsq_f32_e32 v85, v76
	s_addc_u32 s23, s23, s3
	v_lshl_add_u64 v[86:87], s[22:23], 0, v[108:109]
	s_add_i32 s22, s17, s20
	v_mul_f32_e32 v88, 0x45800000, v85
	v_cndmask_b32_e32 v88, v85, v88, vcc
	v_mul_f32_e32 v85, 0x4b800000, v84
	v_cmp_gt_f32_e32 vcc, s7, v84
	ds_read_b128 v[76:79], v112 offset:4160
	s_ashr_i32 s23, s22, 31
	v_cndmask_b32_e32 v84, v84, v85, vcc
	v_rsq_f32_e32 v84, v84
	s_waitcnt lgkmcnt(1)
	v_pk_mul_f32 v[80:81], v[88:89], v[80:81] op_sel_hi:[0,1]
	v_pk_mul_f32 v[82:83], v[88:89], v[82:83] op_sel_hi:[0,1]
	s_lshl_b64 s[22:23], s[22:23], 12
	v_pk_mul_f32 v[82:83], v[2:3], v[82:83]
	v_pk_mul_f32 v[80:81], v[0:1], v[80:81]
	s_add_u32 s21, s10, s22
	global_store_dwordx4 v[86:87], v[80:83], off
	s_addc_u32 s23, s11, s23
	s_add_u32 s22, s21, s2
	v_mul_f32_e32 v80, 0x45800000, v84
	v_cndmask_b32_e32 v84, v84, v80, vcc
	ds_read_b128 v[80:83], v112 offset:5200
	s_waitcnt lgkmcnt(1)
	v_pk_mul_f32 v[76:77], v[84:85], v[76:77] op_sel_hi:[0,1]
	v_pk_mul_f32 v[78:79], v[84:85], v[78:79] op_sel_hi:[0,1]
	s_addc_u32 s23, s23, s3
	v_pk_mul_f32 v[78:79], v[2:3], v[78:79]
	v_pk_mul_f32 v[76:77], v[0:1], v[76:77]
	v_lshl_add_u64 v[84:85], s[22:23], 0, v[108:109]
	global_store_dwordx4 v[84:85], v[76:79], off
	s_add_i32 s22, s18, s20
	s_ashr_i32 s23, s22, 31
	v_mov_b32_e32 v76, v73
	v_mov_b32_e32 v77, v74
	v_mov_b32_e32 v73, v75
	v_mov_b32_e32 v74, v37
	v_mov_b32_e32 v75, v38
	v_mov_b32_e32 v37, v39
	v_pk_add_f32 v[72:73], v[76:77], v[72:73]
	v_pk_add_f32 v[36:37], v[74:75], v[36:37]
	v_mov_b32_e32 v39, v72
	v_mov_b32_e32 v38, v36
	v_mov_b32_e32 v72, v37
	v_pk_add_f32 v[36:37], v[38:39], v[72:73]
	s_lshl_b64 s[22:23], s[22:23], 12
	v_pk_fma_f32 v[72:73], v[36:37], s[6:7], v[110:111] op_sel_hi:[1,0,0]
	s_add_u32 s21, s10, s22
	v_mul_f32_e32 v36, 0x4b800000, v73
	v_cmp_gt_f32_e32 vcc, s7, v73
	s_addc_u32 s23, s11, s23
	s_add_u32 s22, s21, s2
	v_cndmask_b32_e32 v36, v73, v36, vcc
	v_rsq_f32_e32 v73, v36
	s_addc_u32 s23, s23, s3
	s_add_i32 s20, s19, s20
	s_ashr_i32 s21, s20, 31
	v_mul_f32_e32 v74, 0x45800000, v73
	v_cndmask_b32_e32 v74, v73, v74, vcc
	v_mul_f32_e32 v73, 0x4b800000, v72
	v_cmp_gt_f32_e32 vcc, s7, v72
	s_waitcnt lgkmcnt(0)
	v_pk_mul_f32 v[78:79], v[74:75], v[80:81] op_sel_hi:[0,1]
	ds_read_b128 v[36:39], v112 offset:6240
	v_cndmask_b32_e32 v72, v72, v73, vcc
	v_rsq_f32_e32 v80, v72
	s_lshl_b64 s[20:21], s[20:21], 12
	v_pk_mul_f32 v[74:75], v[74:75], v[82:83] op_sel_hi:[0,1]
	s_add_u32 s20, s10, s20
	v_lshl_add_u64 v[76:77], s[22:23], 0, v[108:109]
	v_pk_mul_f32 v[74:75], v[2:3], v[74:75]
	v_pk_mul_f32 v[72:73], v[0:1], v[78:79]
	s_addc_u32 s21, s11, s21
	global_store_dwordx4 v[76:77], v[72:75], off
	s_add_u32 s20, s20, s2
	s_addc_u32 s21, s21, s3
	v_mul_f32_e32 v72, 0x45800000, v80
	v_cndmask_b32_e32 v72, v80, v72, vcc
	s_waitcnt lgkmcnt(0)
	v_pk_mul_f32 v[36:37], v[72:73], v[36:37] op_sel_hi:[0,1]
	v_pk_mul_f32 v[38:39], v[72:73], v[38:39] op_sel_hi:[0,1]
	v_lshl_add_u64 v[72:73], s[20:21], 0, v[108:109]
	s_add_i32 s20, s9, 0x80
	s_add_i32 s21, s16, s20
	s_or_b32 s22, s21, s8
	s_ashr_i32 s23, s22, 31
	s_lshl_b64 s[22:23], s[22:23], 4
	s_add_u32 s22, s4, s22
	v_pk_mul_f32 v[38:39], v[2:3], v[38:39]
	v_pk_mul_f32 v[36:37], v[0:1], v[36:37]
	s_addc_u32 s23, s5, s23
	global_store_dwordx4 v[72:73], v[36:39], off
	s_barrier
	ds_write_b128 v136, v[64:67]
	ds_write_b128 v136, v[60:63] offset:16
	ds_write_b128 v136, v[56:59] offset:512
	ds_write_b128 v136, v[48:51] offset:528
	ds_write_b128 v136, v[52:55] offset:16640
	ds_write_b128 v136, v[44:47] offset:16656
	ds_write_b128 v136, v[40:43] offset:17152
	ds_write_b128 v136, v[68:71] offset:17168
	s_waitcnt lgkmcnt(0)
	s_barrier
	global_load_dwordx4 v[44:47], v113, s[22:23]
	global_load_dwordx4 v[48:51], v113, s[22:23] offset:16
	global_load_dwordx4 v[52:55], v113, s[22:23] offset:32
	global_load_dwordx4 v[56:59], v113, s[22:23] offset:48
	s_or_b32 s22, s21, s13
	s_ashr_i32 s23, s22, 31
	s_lshl_b64 s[22:23], s[22:23], 4
	s_add_u32 s22, s4, s22
	s_addc_u32 s23, s5, s23
	global_load_dwordx4 v[36:39], v113, s[22:23] offset:48
	global_load_dwordx4 v[40:43], v113, s[22:23] offset:32
	global_load_dwordx4 v[60:63], v113, s[22:23] offset:16
	global_load_dwordx4 v[64:67], v113, s[22:23]
	s_add_i32 s22, s12, s20
	s_ashr_i32 s23, s22, 31
	ds_read_b128 v[68:71], v114
	s_lshl_b64 s[22:23], s[22:23], 12
	s_add_u32 s21, s10, s22
	s_addc_u32 s23, s11, s23
	s_add_u32 s22, s21, s2
	s_addc_u32 s23, s23, s3
	s_waitcnt vmcnt(7)
	v_mov_b32_e32 v72, v45
	v_mov_b32_e32 v73, v46
	v_mov_b32_e32 v45, v47
	s_waitcnt vmcnt(6)
	v_mov_b32_e32 v46, v49
	v_mov_b32_e32 v47, v50
	v_mov_b32_e32 v49, v51
	v_pk_add_f32 v[44:45], v[72:73], v[44:45]
	v_pk_add_f32 v[46:47], v[46:47], v[48:49]
	v_mov_b32_e32 v49, v44
	v_mov_b32_e32 v48, v46
	v_mov_b32_e32 v44, v47
	v_pk_add_f32 v[44:45], v[48:49], v[44:45]
	v_lshl_add_u64 v[72:73], s[22:23], 0, v[108:109]
	v_pk_fma_f32 v[48:49], v[44:45], s[6:7], v[110:111] op_sel_hi:[1,0,0]
	s_add_i32 s22, s0, s20
	v_mul_f32_e32 v44, 0x4b800000, v49
	v_cmp_gt_f32_e32 vcc, s7, v49
	s_ashr_i32 s23, s22, 31
	s_lshl_b64 s[22:23], s[22:23], 12
	v_cndmask_b32_e32 v44, v49, v44, vcc
	v_rsq_f32_e32 v49, v44
	ds_read_b128 v[44:47], v112
	s_add_u32 s21, s10, s22
	s_addc_u32 s23, s11, s23
	v_mul_f32_e32 v50, 0x45800000, v49
	v_cndmask_b32_e32 v50, v49, v50, vcc
	v_mul_f32_e32 v49, 0x4b800000, v48
	v_cmp_gt_f32_e32 vcc, s7, v48
	s_waitcnt lgkmcnt(1)
	v_pk_mul_f32 v[68:69], v[68:69], v[50:51] op_sel_hi:[1,0]
	v_pk_mul_f32 v[50:51], v[70:71], v[50:51] op_sel_hi:[1,0]
	v_cndmask_b32_e32 v48, v48, v49, vcc
	v_rsq_f32_e32 v70, v48
	v_pk_mul_f32 v[50:51], v[2:3], v[50:51]
	v_pk_mul_f32 v[48:49], v[0:1], v[68:69]
	global_store_dwordx4 v[72:73], v[48:51], off
	s_add_u32 s22, s21, s2
	s_addc_u32 s23, s23, s3
	v_mul_f32_e32 v48, 0x45800000, v70
	v_cndmask_b32_e32 v68, v70, v48, vcc
	ds_read_b128 v[48:51], v112 offset:1040
	s_waitcnt lgkmcnt(1)
	v_pk_mul_f32 v[44:45], v[44:45], v[68:69] op_sel_hi:[1,0]
	v_pk_mul_f32 v[46:47], v[46:47], v[68:69] op_sel_hi:[1,0]
	v_pk_mul_f32 v[44:45], v[0:1], v[44:45]
	v_pk_mul_f32 v[46:47], v[2:3], v[46:47]
	v_lshl_add_u64 v[68:69], s[22:23], 0, v[108:109]
	global_store_dwordx4 v[68:69], v[44:47], off
	s_add_i32 s22, s1, s20
	s_ashr_i32 s23, s22, 31
	s_waitcnt vmcnt(7)
	v_mov_b32_e32 v44, v53
	v_mov_b32_e32 v45, v54
	v_mov_b32_e32 v53, v55
	s_waitcnt vmcnt(6)
	v_mov_b32_e32 v46, v57
	v_mov_b32_e32 v47, v58
	v_mov_b32_e32 v57, v59
	v_pk_add_f32 v[44:45], v[44:45], v[52:53]
	v_pk_add_f32 v[46:47], v[46:47], v[56:57]
	v_mov_b32_e32 v53, v44
	v_mov_b32_e32 v52, v46
	v_mov_b32_e32 v44, v47
	v_pk_add_f32 v[44:45], v[52:53], v[44:45]
	s_lshl_b64 s[22:23], s[22:23], 12
	v_pk_fma_f32 v[52:53], v[44:45], s[6:7], v[110:111] op_sel_hi:[1,0,0]
	s_add_u32 s21, s10, s22
	v_mul_f32_e32 v44, 0x4b800000, v53
	v_cmp_gt_f32_e32 vcc, s7, v53
	s_addc_u32 s23, s11, s23
	s_add_u32 s22, s21, s2
	v_cndmask_b32_e32 v44, v53, v44, vcc
	v_rsq_f32_e32 v53, v44
	s_addc_u32 s23, s23, s3
	v_lshl_add_u64 v[54:55], s[22:23], 0, v[108:109]
	s_add_i32 s22, s14, s20
	v_mul_f32_e32 v56, 0x45800000, v53
	v_cndmask_b32_e32 v56, v53, v56, vcc
	v_mul_f32_e32 v53, 0x4b800000, v52
	v_cmp_gt_f32_e32 vcc, s7, v52
	ds_read_b128 v[44:47], v112 offset:2080
	s_ashr_i32 s23, s22, 31
	v_cndmask_b32_e32 v52, v52, v53, vcc
	v_rsq_f32_e32 v52, v52
	s_waitcnt lgkmcnt(1)
	v_pk_mul_f32 v[48:49], v[48:49], v[56:57] op_sel_hi:[1,0]
	v_pk_mul_f32 v[50:51], v[50:51], v[56:57] op_sel_hi:[1,0]
	s_lshl_b64 s[22:23], s[22:23], 12
	v_pk_mul_f32 v[50:51], v[2:3], v[50:51]
	v_pk_mul_f32 v[48:49], v[0:1], v[48:49]
	s_add_u32 s21, s10, s22
	global_store_dwordx4 v[54:55], v[48:51], off
	s_addc_u32 s23, s11, s23
	s_add_u32 s22, s21, s2
	v_mul_f32_e32 v48, 0x45800000, v52
	v_cndmask_b32_e32 v52, v52, v48, vcc
	ds_read_b128 v[48:51], v112 offset:3120
	s_waitcnt lgkmcnt(1)
	v_pk_mul_f32 v[44:45], v[44:45], v[52:53] op_sel_hi:[1,0]
	v_pk_mul_f32 v[46:47], v[46:47], v[52:53] op_sel_hi:[1,0]
	s_addc_u32 s23, s23, s3
	v_pk_mul_f32 v[46:47], v[2:3], v[46:47]
	v_pk_mul_f32 v[44:45], v[0:1], v[44:45]
	v_lshl_add_u64 v[52:53], s[22:23], 0, v[108:109]
	global_store_dwordx4 v[52:53], v[44:47], off
	s_add_i32 s22, s15, s20
	s_ashr_i32 s23, s22, 31
	s_waitcnt vmcnt(4)
	v_mov_b32_e32 v44, v65
	v_mov_b32_e32 v45, v66
	v_mov_b32_e32 v65, v67
	v_mov_b32_e32 v46, v61
	v_mov_b32_e32 v47, v62
	v_mov_b32_e32 v61, v63
	v_pk_add_f32 v[44:45], v[44:45], v[64:65]
	v_pk_add_f32 v[46:47], v[46:47], v[60:61]
	v_mov_b32_e32 v53, v44
	v_mov_b32_e32 v52, v46
	v_mov_b32_e32 v44, v47
	v_pk_add_f32 v[44:45], v[52:53], v[44:45]
	s_lshl_b64 s[22:23], s[22:23], 12
	v_pk_fma_f32 v[52:53], v[44:45], s[6:7], v[110:111] op_sel_hi:[1,0,0]
	s_add_u32 s21, s10, s22
	v_mul_f32_e32 v44, 0x4b800000, v53
	v_cmp_gt_f32_e32 vcc, s7, v53
	s_addc_u32 s23, s11, s23
	s_add_u32 s22, s21, s2
	v_cndmask_b32_e32 v44, v53, v44, vcc
	v_rsq_f32_e32 v53, v44
	s_addc_u32 s23, s23, s3
	v_lshl_add_u64 v[54:55], s[22:23], 0, v[108:109]
	s_add_i32 s22, s17, s20
	v_mul_f32_e32 v56, 0x45800000, v53
	v_cndmask_b32_e32 v56, v53, v56, vcc
	v_mul_f32_e32 v53, 0x4b800000, v52
	v_cmp_gt_f32_e32 vcc, s7, v52
	ds_read_b128 v[44:47], v112 offset:4160
	s_ashr_i32 s23, s22, 31
	v_cndmask_b32_e32 v52, v52, v53, vcc
	v_rsq_f32_e32 v52, v52
	s_waitcnt lgkmcnt(1)
	v_pk_mul_f32 v[48:49], v[56:57], v[48:49] op_sel_hi:[0,1]
	v_pk_mul_f32 v[50:51], v[56:57], v[50:51] op_sel_hi:[0,1]
	s_lshl_b64 s[22:23], s[22:23], 12
	v_pk_mul_f32 v[50:51], v[2:3], v[50:51]
	v_pk_mul_f32 v[48:49], v[0:1], v[48:49]
	s_add_u32 s21, s10, s22
	global_store_dwordx4 v[54:55], v[48:51], off
	s_addc_u32 s23, s11, s23
	s_add_u32 s22, s21, s2
	v_mul_f32_e32 v48, 0x45800000, v52
	v_cndmask_b32_e32 v52, v52, v48, vcc
	ds_read_b128 v[48:51], v112 offset:5200
	s_waitcnt lgkmcnt(1)
	v_pk_mul_f32 v[44:45], v[52:53], v[44:45] op_sel_hi:[0,1]
	v_pk_mul_f32 v[46:47], v[52:53], v[46:47] op_sel_hi:[0,1]
	s_addc_u32 s23, s23, s3
	v_pk_mul_f32 v[46:47], v[2:3], v[46:47]
	v_pk_mul_f32 v[44:45], v[0:1], v[44:45]
	v_lshl_add_u64 v[52:53], s[22:23], 0, v[108:109]
	global_store_dwordx4 v[52:53], v[44:47], off
	s_add_i32 s22, s18, s20
	s_ashr_i32 s23, s22, 31
	v_mov_b32_e32 v44, v41
	v_mov_b32_e32 v45, v42
	v_mov_b32_e32 v41, v43
	v_mov_b32_e32 v42, v37
	v_mov_b32_e32 v43, v38
	v_mov_b32_e32 v37, v39
	v_pk_add_f32 v[40:41], v[44:45], v[40:41]
	v_pk_add_f32 v[36:37], v[42:43], v[36:37]
	v_mov_b32_e32 v39, v40
	v_mov_b32_e32 v38, v36
	v_mov_b32_e32 v40, v37
	v_pk_add_f32 v[36:37], v[38:39], v[40:41]
	s_lshl_b64 s[22:23], s[22:23], 12
	v_pk_fma_f32 v[40:41], v[36:37], s[6:7], v[110:111] op_sel_hi:[1,0,0]
	s_add_u32 s21, s10, s22
	v_mul_f32_e32 v36, 0x4b800000, v41
	v_cmp_gt_f32_e32 vcc, s7, v41
	s_addc_u32 s23, s11, s23
	s_add_u32 s22, s21, s2
	v_cndmask_b32_e32 v36, v41, v36, vcc
	v_rsq_f32_e32 v41, v36
	s_addc_u32 s23, s23, s3
	s_add_i32 s20, s19, s20
	s_ashr_i32 s21, s20, 31
	v_mul_f32_e32 v42, 0x45800000, v41
	v_cndmask_b32_e32 v42, v41, v42, vcc
	v_mul_f32_e32 v41, 0x4b800000, v40
	v_cmp_gt_f32_e32 vcc, s7, v40
	s_waitcnt lgkmcnt(0)
	v_pk_mul_f32 v[46:47], v[42:43], v[48:49] op_sel_hi:[0,1]
	s_lshl_b64 s[20:21], s[20:21], 12
	v_cndmask_b32_e32 v40, v40, v41, vcc
	v_rsq_f32_e32 v48, v40
	ds_read_b128 v[36:39], v112 offset:6240
	s_add_u32 s20, s10, s20
	v_pk_mul_f32 v[42:43], v[42:43], v[50:51] op_sel_hi:[0,1]
	s_addc_u32 s21, s11, s21
	v_lshl_add_u64 v[44:45], s[22:23], 0, v[108:109]
	v_pk_mul_f32 v[42:43], v[2:3], v[42:43]
	v_pk_mul_f32 v[40:41], v[0:1], v[46:47]
	s_add_u32 s20, s20, s2
	global_store_dwordx4 v[44:45], v[40:43], off
	s_addc_u32 s21, s21, s3
	s_addk_i32 s9, 0xa0
	v_mul_f32_e32 v40, 0x45800000, v48
	v_cndmask_b32_e32 v40, v48, v40, vcc
	s_add_i32 s16, s16, s9
	s_waitcnt lgkmcnt(0)
	v_pk_mul_f32 v[36:37], v[40:41], v[36:37] op_sel_hi:[0,1]
	v_pk_mul_f32 v[38:39], v[40:41], v[38:39] op_sel_hi:[0,1]
	v_lshl_add_u64 v[40:41], s[20:21], 0, v[108:109]
	s_or_b32 s20, s16, s8
	s_ashr_i32 s21, s20, 31
	s_lshl_b64 s[20:21], s[20:21], 4
	s_add_u32 s20, s4, s20
	v_pk_mul_f32 v[38:39], v[2:3], v[38:39]
	v_pk_mul_f32 v[36:37], v[0:1], v[36:37]
	s_addc_u32 s21, s5, s21
	global_store_dwordx4 v[40:41], v[36:39], off
	s_barrier
	ds_write_b128 v136, v[32:35]
	ds_write_b128 v136, v[28:31] offset:16
	ds_write_b128 v136, v[24:27] offset:512
	ds_write_b128 v136, v[16:19] offset:528
	ds_write_b128 v136, v[20:23] offset:16640
	ds_write_b128 v136, v[12:15] offset:16656
	ds_write_b128 v136, v[8:11] offset:17152
	ds_write_b128 v136, v[4:7] offset:17168
	s_waitcnt lgkmcnt(0)
	s_barrier
	global_load_dwordx4 v[12:15], v113, s[20:21]
	global_load_dwordx4 v[16:19], v113, s[20:21] offset:16
	global_load_dwordx4 v[20:23], v113, s[20:21] offset:32
	global_load_dwordx4 v[24:27], v113, s[20:21] offset:48
	s_or_b32 s20, s16, s13
	s_ashr_i32 s21, s20, 31
	s_lshl_b64 s[20:21], s[20:21], 4
	s_add_u32 s4, s4, s20
	s_addc_u32 s5, s5, s21
	global_load_dwordx4 v[4:7], v113, s[4:5] offset:48
	global_load_dwordx4 v[8:11], v113, s[4:5] offset:32
	global_load_dwordx4 v[28:31], v113, s[4:5] offset:16
	global_load_dwordx4 v[32:35], v113, s[4:5]
	s_add_i32 s4, s12, s9
	s_ashr_i32 s5, s4, 31
	ds_read_b128 v[36:39], v114
	s_lshl_b64 s[4:5], s[4:5], 12
	s_add_u32 s4, s10, s4
	s_addc_u32 s5, s11, s5
	s_add_u32 s4, s4, s2
	s_addc_u32 s5, s5, s3
	s_waitcnt vmcnt(7)
	v_mov_b32_e32 v40, v13
	v_mov_b32_e32 v41, v14
	v_mov_b32_e32 v13, v15
	s_waitcnt vmcnt(6)
	v_mov_b32_e32 v14, v17
	v_mov_b32_e32 v15, v18
	v_mov_b32_e32 v17, v19
	v_pk_add_f32 v[12:13], v[40:41], v[12:13]
	v_pk_add_f32 v[14:15], v[14:15], v[16:17]
	v_mov_b32_e32 v17, v12
	v_mov_b32_e32 v16, v14
	v_mov_b32_e32 v12, v15
	v_pk_add_f32 v[12:13], v[16:17], v[12:13]
	v_lshl_add_u64 v[40:41], s[4:5], 0, v[108:109]
	v_pk_fma_f32 v[16:17], v[12:13], s[6:7], v[110:111] op_sel_hi:[1,0,0]
	s_add_i32 s4, s0, s9
	v_mul_f32_e32 v12, 0x4b800000, v17
	v_cmp_gt_f32_e32 vcc, s7, v17
	s_ashr_i32 s5, s4, 31
	s_lshl_b64 s[4:5], s[4:5], 12
	v_cndmask_b32_e32 v12, v17, v12, vcc
	v_rsq_f32_e32 v17, v12
	ds_read_b128 v[12:15], v112
	s_add_u32 s0, s10, s4
	s_addc_u32 s5, s11, s5
	v_mul_f32_e32 v18, 0x45800000, v17
	v_cndmask_b32_e32 v18, v17, v18, vcc
	v_mul_f32_e32 v17, 0x4b800000, v16
	v_cmp_gt_f32_e32 vcc, s7, v16
	s_waitcnt lgkmcnt(1)
	v_pk_mul_f32 v[36:37], v[36:37], v[18:19] op_sel_hi:[1,0]
	v_pk_mul_f32 v[18:19], v[38:39], v[18:19] op_sel_hi:[1,0]
	v_cndmask_b32_e32 v16, v16, v17, vcc
	v_rsq_f32_e32 v38, v16
	v_pk_mul_f32 v[18:19], v[2:3], v[18:19]
	v_pk_mul_f32 v[16:17], v[0:1], v[36:37]
	global_store_dwordx4 v[40:41], v[16:19], off
	s_add_u32 s4, s0, s2
	s_addc_u32 s5, s5, s3
	v_mul_f32_e32 v16, 0x45800000, v38
	v_cndmask_b32_e32 v36, v38, v16, vcc
	ds_read_b128 v[16:19], v112 offset:1040
	s_waitcnt lgkmcnt(1)
	v_pk_mul_f32 v[12:13], v[12:13], v[36:37] op_sel_hi:[1,0]
	v_pk_mul_f32 v[14:15], v[14:15], v[36:37] op_sel_hi:[1,0]
	v_pk_mul_f32 v[12:13], v[0:1], v[12:13]
	v_pk_mul_f32 v[14:15], v[2:3], v[14:15]
	v_lshl_add_u64 v[36:37], s[4:5], 0, v[108:109]
	global_store_dwordx4 v[36:37], v[12:15], off
	s_add_i32 s0, s1, s9
	s_ashr_i32 s1, s0, 31
	s_waitcnt vmcnt(7)
	v_mov_b32_e32 v12, v21
	v_mov_b32_e32 v13, v22
	v_mov_b32_e32 v21, v23
	s_waitcnt vmcnt(6)
	v_mov_b32_e32 v14, v25
	v_mov_b32_e32 v15, v26
	v_mov_b32_e32 v25, v27
	v_pk_add_f32 v[12:13], v[12:13], v[20:21]
	v_pk_add_f32 v[14:15], v[14:15], v[24:25]
	v_mov_b32_e32 v21, v12
	v_mov_b32_e32 v20, v14
	v_mov_b32_e32 v12, v15
	v_pk_add_f32 v[12:13], v[20:21], v[12:13]
	s_lshl_b64 s[0:1], s[0:1], 12
	v_pk_fma_f32 v[20:21], v[12:13], s[6:7], v[110:111] op_sel_hi:[1,0,0]
	s_add_u32 s0, s10, s0
	v_mul_f32_e32 v12, 0x4b800000, v21
	v_cmp_gt_f32_e32 vcc, s7, v21
	s_addc_u32 s1, s11, s1
	s_add_u32 s0, s0, s2
	v_cndmask_b32_e32 v12, v21, v12, vcc
	v_rsq_f32_e32 v21, v12
	s_addc_u32 s1, s1, s3
	v_lshl_add_u64 v[22:23], s[0:1], 0, v[108:109]
	s_add_i32 s0, s14, s9
	v_mul_f32_e32 v24, 0x45800000, v21
	v_cndmask_b32_e32 v24, v21, v24, vcc
	v_mul_f32_e32 v21, 0x4b800000, v20
	v_cmp_gt_f32_e32 vcc, s7, v20
	ds_read_b128 v[12:15], v112 offset:2080
	s_ashr_i32 s1, s0, 31
	v_cndmask_b32_e32 v20, v20, v21, vcc
	v_rsq_f32_e32 v20, v20
	s_waitcnt lgkmcnt(1)
	v_pk_mul_f32 v[16:17], v[16:17], v[24:25] op_sel_hi:[1,0]
	v_pk_mul_f32 v[18:19], v[18:19], v[24:25] op_sel_hi:[1,0]
	s_lshl_b64 s[0:1], s[0:1], 12
	v_pk_mul_f32 v[18:19], v[2:3], v[18:19]
	v_pk_mul_f32 v[16:17], v[0:1], v[16:17]
	s_add_u32 s0, s10, s0
	global_store_dwordx4 v[22:23], v[16:19], off
	s_addc_u32 s1, s11, s1
	s_add_u32 s0, s0, s2
	v_mul_f32_e32 v16, 0x45800000, v20
	v_cndmask_b32_e32 v20, v20, v16, vcc
	ds_read_b128 v[16:19], v112 offset:3120
	s_waitcnt lgkmcnt(1)
	v_pk_mul_f32 v[12:13], v[12:13], v[20:21] op_sel_hi:[1,0]
	v_pk_mul_f32 v[14:15], v[14:15], v[20:21] op_sel_hi:[1,0]
	s_addc_u32 s1, s1, s3
	v_pk_mul_f32 v[14:15], v[2:3], v[14:15]
	v_pk_mul_f32 v[12:13], v[0:1], v[12:13]
	v_lshl_add_u64 v[20:21], s[0:1], 0, v[108:109]
	global_store_dwordx4 v[20:21], v[12:15], off
	s_add_i32 s0, s15, s9
	s_ashr_i32 s1, s0, 31
	s_waitcnt vmcnt(4)
	v_mov_b32_e32 v12, v33
	v_mov_b32_e32 v13, v34
	v_mov_b32_e32 v33, v35
	v_mov_b32_e32 v14, v29
	v_mov_b32_e32 v15, v30
	v_mov_b32_e32 v29, v31
	v_pk_add_f32 v[12:13], v[12:13], v[32:33]
	v_pk_add_f32 v[14:15], v[14:15], v[28:29]
	v_mov_b32_e32 v21, v12
	v_mov_b32_e32 v20, v14
	v_mov_b32_e32 v12, v15
	v_pk_add_f32 v[12:13], v[20:21], v[12:13]
	s_lshl_b64 s[0:1], s[0:1], 12
	v_pk_fma_f32 v[20:21], v[12:13], s[6:7], v[110:111] op_sel_hi:[1,0,0]
	s_add_u32 s0, s10, s0
	v_mul_f32_e32 v12, 0x4b800000, v21
	v_cmp_gt_f32_e32 vcc, s7, v21
	s_addc_u32 s1, s11, s1
	s_add_u32 s0, s0, s2
	v_cndmask_b32_e32 v12, v21, v12, vcc
	v_rsq_f32_e32 v21, v12
	s_addc_u32 s1, s1, s3
	v_lshl_add_u64 v[22:23], s[0:1], 0, v[108:109]
	s_add_i32 s0, s17, s9
	v_mul_f32_e32 v24, 0x45800000, v21
	v_cndmask_b32_e32 v24, v21, v24, vcc
	v_mul_f32_e32 v21, 0x4b800000, v20
	v_cmp_gt_f32_e32 vcc, s7, v20
	ds_read_b128 v[12:15], v112 offset:4160
	s_ashr_i32 s1, s0, 31
	v_cndmask_b32_e32 v20, v20, v21, vcc
	v_rsq_f32_e32 v20, v20
	s_waitcnt lgkmcnt(1)
	v_pk_mul_f32 v[16:17], v[24:25], v[16:17] op_sel_hi:[0,1]
	v_pk_mul_f32 v[18:19], v[24:25], v[18:19] op_sel_hi:[0,1]
	s_lshl_b64 s[0:1], s[0:1], 12
	v_pk_mul_f32 v[18:19], v[2:3], v[18:19]
	v_pk_mul_f32 v[16:17], v[0:1], v[16:17]
	s_add_u32 s0, s10, s0
	global_store_dwordx4 v[22:23], v[16:19], off
	s_addc_u32 s1, s11, s1
	s_add_u32 s0, s0, s2
	v_mul_f32_e32 v16, 0x45800000, v20
	v_cndmask_b32_e32 v20, v20, v16, vcc
	ds_read_b128 v[16:19], v112 offset:5200
	s_waitcnt lgkmcnt(1)
	v_pk_mul_f32 v[12:13], v[20:21], v[12:13] op_sel_hi:[0,1]
	v_pk_mul_f32 v[14:15], v[20:21], v[14:15] op_sel_hi:[0,1]
	s_addc_u32 s1, s1, s3
	v_pk_mul_f32 v[14:15], v[2:3], v[14:15]
	v_pk_mul_f32 v[12:13], v[0:1], v[12:13]
	v_lshl_add_u64 v[20:21], s[0:1], 0, v[108:109]
	global_store_dwordx4 v[20:21], v[12:15], off
	s_add_i32 s0, s18, s9
	s_ashr_i32 s1, s0, 31
	v_mov_b32_e32 v12, v9
	v_mov_b32_e32 v13, v10
	v_mov_b32_e32 v9, v11
	v_mov_b32_e32 v10, v5
	v_mov_b32_e32 v11, v6
	v_mov_b32_e32 v5, v7
	v_pk_add_f32 v[8:9], v[12:13], v[8:9]
	v_pk_add_f32 v[4:5], v[10:11], v[4:5]
	v_mov_b32_e32 v7, v8
	v_mov_b32_e32 v6, v4
	v_mov_b32_e32 v8, v5
	v_pk_add_f32 v[4:5], v[6:7], v[8:9]
	s_lshl_b64 s[0:1], s[0:1], 12
	v_pk_fma_f32 v[8:9], v[4:5], s[6:7], v[110:111] op_sel_hi:[1,0,0]
	s_add_u32 s0, s10, s0
	v_mul_f32_e32 v4, 0x4b800000, v9
	v_cmp_gt_f32_e32 vcc, s7, v9
	s_addc_u32 s1, s11, s1
	s_add_u32 s0, s0, s2
	v_cndmask_b32_e32 v4, v9, v4, vcc
	v_rsq_f32_e32 v9, v4
	s_addc_u32 s1, s1, s3
	v_lshl_add_u64 v[12:13], s[0:1], 0, v[108:109]
	s_add_i32 s0, s19, s9
	v_mul_f32_e32 v10, 0x45800000, v9
	v_cndmask_b32_e32 v10, v9, v10, vcc
	v_mul_f32_e32 v9, 0x4b800000, v8
	v_cmp_gt_f32_e32 vcc, s7, v8
	s_waitcnt lgkmcnt(0)
	v_pk_mul_f32 v[14:15], v[10:11], v[16:17] op_sel_hi:[0,1]
	ds_read_b128 v[4:7], v112 offset:6240
	v_cndmask_b32_e32 v8, v8, v9, vcc
	v_rsq_f32_e32 v16, v8
	s_ashr_i32 s1, s0, 31
	v_pk_mul_f32 v[10:11], v[10:11], v[18:19] op_sel_hi:[0,1]
	s_lshl_b64 s[0:1], s[0:1], 12
	v_pk_mul_f32 v[10:11], v[2:3], v[10:11]
	v_pk_mul_f32 v[8:9], v[0:1], v[14:15]
	s_add_u32 s0, s10, s0
	global_store_dwordx4 v[12:13], v[8:11], off
	s_addc_u32 s1, s11, s1
	s_add_u32 s0, s0, s2
	v_mul_f32_e32 v8, 0x45800000, v16
	v_cndmask_b32_e32 v8, v16, v8, vcc
	s_waitcnt lgkmcnt(0)
	v_pk_mul_f32 v[4:5], v[8:9], v[4:5] op_sel_hi:[0,1]
	v_pk_mul_f32 v[6:7], v[8:9], v[6:7] op_sel_hi:[0,1]
	s_addc_u32 s1, s1, s3
	v_pk_mul_f32 v[2:3], v[2:3], v[6:7]
	v_pk_mul_f32 v[0:1], v[0:1], v[4:5]
	v_lshl_add_u64 v[4:5], s[0:1], 0, v[108:109]
	global_store_dwordx4 v[4:5], v[0:3], off
	s_barrier
